# LRU final pass: the 32 LDS reads feeding the 16-step scan hoisted in front of the dependent fma chain
# baseline (speedup 1.0000x reference)
; __device__ __forceinline__ bf16_t f2bf(float f) { return (bf16_t)(cvt_pk_bf16(f, 0.f) & 0xffffu); }
; __device__ __forceinline__ float bf2f(bf16_t b) { return __uint_as_float(((unsigned)b) << 16); }
; __device__ __forceinline__ float sigmoidf_(float x) { return 1.0f / (1.0f + __expf(-x)); }
; template <bool FINAL>
; __device__ __forceinline__ void lru_item(const Ctx& C, int l, int item) {
;     ...
;         for (int s4 = 0; s4 < 4; ++s4) { const int tt = z ? 3 - s4 : s4;
;             const bf16_t* xrow = xc + (16 * tt + fr) * XCP + n * 64 + 8 * quad;
;             const bf16x8 xa0 = *(const bf16x8*)xrow, xa1 = *(const bf16x8*)(xrow + 32);
; #pragma unroll
;             for (int dt = 0; dt < 4; ++dt) {
;                 f32x4 Da = {0.f, 0.f, 0.f, 0.f}, Dx = {0.f, 0.f, 0.f, 0.f};
;                 Da = __builtin_amdgcn_mfma_f32_16x16x32_bf16(xa0, Bw[0][dt][0], Da, 0, 0, 0); Da = __builtin_amdgcn_mfma_f32_16x16x32_bf16(xa1, Bw[0][dt][1], Da, 0, 0, 0);
;                 Dx = __builtin_amdgcn_mfma_f32_16x16x32_bf16(xa0, Bw[1][dt][0], Dx, 0, 0, 0); Dx = __builtin_amdgcn_mfma_f32_16x16x32_bf16(xa1, Bw[1][dt][1], Dx, 0, 0, 0);
; #pragma unroll
;                 for (int r = 0; r < 4; ++r) { const int tloc = 4 * quad + r, d = 16 * dt + fr;
;                     const float rg = sigmoidf_(Da[r] + bav[dt]), ig = sigmoidf_(Dx[r] + bxv[dt]), la = -8.0f * rg * spv[dt], a = __expf(la);
;                     const float x = bf2f(xc[(16 * tt + tloc) * XCP + n * 64 + d]);
;                     Al[tloc * 68 + d] = a; Ul[tloc * 68 + d] = f2bf(sqrtf(fmaxf(1.0f - a * a, 0.f)) * ig * x); }
.LBB0_681:
	s_and_b64 s[0:1], s[4:5], exec
	s_cselect_b32 s0, s9, s51
	s_lshl_b32 s52, s0, 4
	v_or_b32_e32 v66, s52, v97
	v_mad_u64_u32 v[66:67], s[0:1], v66, s58, v[96:97]
	ds_read_b128 v[70:73], v66
	ds_read_b128 v[66:69], v66 offset:64
	s_add_i32 s9, s9, 1
	s_add_i32 s51, s51, -1
	s_waitcnt lgkmcnt(1)
	v_mfma_f32_16x16x32_bf16 v[74:77], v[70:73], v[0:3], 0
	s_waitcnt lgkmcnt(0)
	v_mfma_f32_16x16x32_bf16 v[74:77], v[66:69], v[16:19], v[74:77]
	v_mfma_f32_16x16x32_bf16 v[104:107], v[70:73], v[32:35], 0
	v_mfma_f32_16x16x32_bf16 v[174:177], v[66:69], v[48:51], v[104:107]
	s_nop 5
	v_add_f32_e32 v74, v64, v74
	v_mul_f32_e32 v74, 0xbfb8aa3b, v74
	v_exp_f32_e32 v74, v74
	s_nop 0
	v_add_f32_e32 v74, 1.0, v74
	s_nop 0
	v_rcp_f32_e32 v74, v74
	v_add_f32_e32 v104, v162, v174
	v_mul_f32_e32 v104, 0xbfb8aa3b, v104
	v_exp_f32_e32 v104, v104
	v_mul_f32_e32 v74, 0xc1000000, v74
	v_mul_f32_e32 v74, v163, v74
	v_mul_f32_e32 v74, 0x3fb8aa3b, v74
	v_add_f32_e32 v104, 1.0, v104
	v_exp_f32_e32 v74, v74
	ds_write_b32 v114, v74 offset:33792
	v_fma_f32 v74, -v74, v74, 1.0
	v_max_f32_e32 v74, 0, v74
	v_rcp_f32_e32 v104, v104
	v_or_b32_e32 v105, s52, v112
	v_mad_u64_u32 v[110:111], s[0:1], v105, s58, v[98:99]
	ds_read_u16 v105, v110
	s_waitcnt lgkmcnt(0)
	v_lshlrev_b32_e32 v105, 16, v105
	s_nop 1
	v_sqrt_f32_e32 v74, v74
	s_nop 0
	v_mul_f32_e32 v74, v104, v74
	v_mul_f32_e32 v74, v74, v105
	v_cvt_pk_bf16_f32 v74, v74, s0
	ds_write_b16 v87, v74 offset:38144
	v_add_f32_e32 v74, v64, v75
	v_mul_f32_e32 v74, 0xbfb8aa3b, v74
	v_exp_f32_e32 v74, v74
	s_nop 0
	v_add_f32_e32 v74, 1.0, v74
	s_nop 0
	v_rcp_f32_e32 v74, v74
	v_add_f32_e32 v75, v162, v175
	v_mul_f32_e32 v75, 0xbfb8aa3b, v75
	v_exp_f32_e32 v75, v75
	v_mul_f32_e32 v74, 0xc1000000, v74
	v_mul_f32_e32 v74, v163, v74
	v_mul_f32_e32 v74, 0x3fb8aa3b, v74
	v_add_f32_e32 v75, 1.0, v75
	v_exp_f32_e32 v74, v74
	ds_write_b32 v116, v74 offset:33792
	v_fma_f32 v74, -v74, v74, 1.0
	v_max_f32_e32 v74, 0, v74
	v_rcp_f32_e32 v75, v75
	v_or_b32_e32 v104, s52, v115
	v_mad_u64_u32 v[108:109], s[0:1], v104, s58, v[98:99]
	ds_read_u16 v104, v108
	s_waitcnt lgkmcnt(0)
	v_lshlrev_b32_e32 v104, 16, v104
	s_nop 1
	v_sqrt_f32_e32 v74, v74
	s_nop 0
	v_mul_f32_e32 v74, v75, v74
	v_mul_f32_e32 v74, v74, v104
	v_cvt_pk_bf16_f32 v74, v74, s0
	ds_write_b16 v144, v74 offset:38144
	v_add_f32_e32 v74, v64, v76
	v_mul_f32_e32 v74, 0xbfb8aa3b, v74
	v_exp_f32_e32 v74, v74
	s_nop 0
	v_add_f32_e32 v74, 1.0, v74
	s_nop 0
	v_rcp_f32_e32 v74, v74
	v_add_f32_e32 v75, v162, v176
	v_mul_f32_e32 v75, 0xbfb8aa3b, v75
	v_exp_f32_e32 v75, v75
	v_mul_f32_e32 v74, 0xc1000000, v74
	v_mul_f32_e32 v74, v163, v74
	v_mul_f32_e32 v74, 0x3fb8aa3b, v74
	v_add_f32_e32 v75, 1.0, v75
	v_exp_f32_e32 v74, v74
	ds_write_b32 v118, v74 offset:33792
	v_fma_f32 v74, -v74, v74, 1.0
	v_max_f32_e32 v74, 0, v74
	v_rcp_f32_e32 v75, v75
	v_or_b32_e32 v76, s52, v117
	v_mad_u64_u32 v[106:107], s[0:1], v76, s58, v[98:99]
	ds_read_u16 v76, v106
	s_waitcnt lgkmcnt(0)
	v_lshlrev_b32_e32 v76, 16, v76
	s_nop 1
	v_sqrt_f32_e32 v74, v74
	s_nop 0
	v_mul_f32_e32 v74, v75, v74
	v_mul_f32_e32 v74, v74, v76
	v_cvt_pk_bf16_f32 v74, v74, s0
	ds_write_b16 v145, v74 offset:38144
	v_add_f32_e32 v74, v64, v77
	v_mul_f32_e32 v74, 0xbfb8aa3b, v74
	v_exp_f32_e32 v74, v74
	s_nop 0
	v_add_f32_e32 v74, 1.0, v74
	s_nop 0
	v_rcp_f32_e32 v74, v74
	v_add_f32_e32 v75, v162, v177
	v_mul_f32_e32 v75, 0xbfb8aa3b, v75
	v_exp_f32_e32 v75, v75
	v_mul_f32_e32 v74, 0xc1000000, v74
	v_mul_f32_e32 v74, v163, v74
	v_mul_f32_e32 v74, 0x3fb8aa3b, v74
	v_add_f32_e32 v75, 1.0, v75
	v_exp_f32_e32 v74, v74
	v_mfma_f32_16x16x32_bf16 v[174:177], v[70:73], v[36:39], 0
	ds_write_b32 v120, v74 offset:33792
	v_fma_f32 v74, -v74, v74, 1.0
	v_max_f32_e32 v74, 0, v74
	v_rcp_f32_e32 v75, v75
	v_or_b32_e32 v76, s52, v119
	v_mad_u64_u32 v[104:105], s[0:1], v76, s58, v[98:99]
	ds_read_u16 v76, v104
	v_mfma_f32_16x16x32_bf16 v[174:177], v[66:69], v[52:55], v[174:177]
	s_waitcnt lgkmcnt(0)
	v_lshlrev_b32_e32 v76, 16, v76
	s_nop 1
	v_sqrt_f32_e32 v74, v74
	s_nop 0
	v_mul_f32_e32 v74, v75, v74
	v_mul_f32_e32 v74, v74, v76
	v_cvt_pk_bf16_f32 v74, v74, s0
	ds_write_b16 v146, v74 offset:38144
	v_mfma_f32_16x16x32_bf16 v[74:77], v[70:73], v[4:7], 0
	v_mfma_f32_16x16x32_bf16 v[74:77], v[66:69], v[20:23], v[74:77]
	s_nop 7
	v_add_f32_e32 v74, v164, v74
	v_mul_f32_e32 v74, 0xbfb8aa3b, v74
	v_exp_f32_e32 v74, v74
	s_nop 0
	v_add_f32_e32 v74, 1.0, v74
	s_nop 0
	v_rcp_f32_e32 v74, v74
	v_add_f32_e32 v105, v165, v174
	v_mul_f32_e32 v105, 0xbfb8aa3b, v105
	v_exp_f32_e32 v105, v105
	v_mul_f32_e32 v74, 0xc1000000, v74
	v_mul_f32_e32 v74, v166, v74
	v_mul_f32_e32 v74, 0x3fb8aa3b, v74
	v_add_f32_e32 v105, 1.0, v105
	v_exp_f32_e32 v74, v74
	ds_write_b32 v114, v74 offset:33856
	v_fma_f32 v74, -v74, v74, 1.0
	v_max_f32_e32 v74, 0, v74
	v_rcp_f32_e32 v105, v105
	ds_read_u16 v107, v110 offset:32
	s_waitcnt lgkmcnt(0)
	v_lshlrev_b32_e32 v107, 16, v107
	s_nop 1
	s_nop 1
	v_sqrt_f32_e32 v74, v74
	s_nop 0
	v_mul_f32_e32 v74, v105, v74
	v_mul_f32_e32 v74, v74, v107
	v_cvt_pk_bf16_f32 v74, v74, s0
	ds_write_b16 v121, v74 offset:38176
	v_add_f32_e32 v74, v164, v75
	v_mul_f32_e32 v74, 0xbfb8aa3b, v74
	v_exp_f32_e32 v74, v74
	s_nop 0
	v_add_f32_e32 v74, 1.0, v74
	s_nop 0
	v_rcp_f32_e32 v74, v74
	v_add_f32_e32 v75, v165, v175
	v_mul_f32_e32 v75, 0xbfb8aa3b, v75
	v_exp_f32_e32 v75, v75
	v_mul_f32_e32 v74, 0xc1000000, v74
	v_mul_f32_e32 v74, v166, v74
	v_mul_f32_e32 v74, 0x3fb8aa3b, v74
	v_add_f32_e32 v75, 1.0, v75
	v_exp_f32_e32 v74, v74
	ds_write_b32 v116, v74 offset:33856
	v_fma_f32 v74, -v74, v74, 1.0
	v_max_f32_e32 v74, 0, v74
	v_rcp_f32_e32 v75, v75
	ds_read_u16 v105, v108 offset:32
	s_waitcnt lgkmcnt(0)
; __device__ __forceinline__ bf16_t f2bf(float f) { return (bf16_t)(cvt_pk_bf16(f, 0.f) & 0xffffu); }
; __device__ __forceinline__ float bf2f(bf16_t b) { return __uint_as_float(((unsigned)b) << 16); }
; __device__ __forceinline__ float sigmoidf_(float x) { return 1.0f / (1.0f + __expf(-x)); }
; template <bool FINAL>
; __device__ __forceinline__ void lru_item(const Ctx& C, int l, int item) {
;     ...
;             for (int dt = 0; dt < 4; ++dt) {
;                 f32x4 Da = {0.f, 0.f, 0.f, 0.f}, Dx = {0.f, 0.f, 0.f, 0.f};
;                 Da = __builtin_amdgcn_mfma_f32_16x16x32_bf16(xa0, Bw[0][dt][0], Da, 0, 0, 0); Da = __builtin_amdgcn_mfma_f32_16x16x32_bf16(xa1, Bw[0][dt][1], Da, 0, 0, 0);
;                 Dx = __builtin_amdgcn_mfma_f32_16x16x32_bf16(xa0, Bw[1][dt][0], Dx, 0, 0, 0); Dx = __builtin_amdgcn_mfma_f32_16x16x32_bf16(xa1, Bw[1][dt][1], Dx, 0, 0, 0);
; #pragma unroll
;                 for (int r = 0; r < 4; ++r) { const int tloc = 4 * quad + r, d = 16 * dt + fr;
;                     const float rg = sigmoidf_(Da[r] + bav[dt]), ig = sigmoidf_(Dx[r] + bxv[dt]), la = -8.0f * rg * spv[dt], a = __expf(la);
;                     const float x = bf2f(xc[(16 * tt + tloc) * XCP + n * 64 + d]);
;                     Al[tloc * 68 + d] = a; Ul[tloc * 68 + d] = f2bf(sqrtf(fmaxf(1.0f - a * a, 0.f)) * ig * x); }
	v_lshlrev_b32_e32 v105, 16, v105
	s_nop 1
	s_nop 1
	v_sqrt_f32_e32 v74, v74
	s_nop 0
	v_mul_f32_e32 v74, v75, v74
	v_mul_f32_e32 v74, v74, v105
	v_cvt_pk_bf16_f32 v74, v74, s0
	ds_write_b16 v122, v74 offset:38176
	v_add_f32_e32 v74, v164, v76
	v_mul_f32_e32 v74, 0xbfb8aa3b, v74
	v_exp_f32_e32 v74, v74
	s_nop 0
	v_add_f32_e32 v74, 1.0, v74
	s_nop 0
	v_rcp_f32_e32 v74, v74
	v_add_f32_e32 v75, v165, v176
	v_mul_f32_e32 v75, 0xbfb8aa3b, v75
	v_exp_f32_e32 v75, v75
	v_mul_f32_e32 v74, 0xc1000000, v74
	v_mul_f32_e32 v74, v166, v74
	v_mul_f32_e32 v74, 0x3fb8aa3b, v74
	v_add_f32_e32 v75, 1.0, v75
	v_exp_f32_e32 v74, v74
	ds_write_b32 v118, v74 offset:33856
	v_fma_f32 v74, -v74, v74, 1.0
	v_max_f32_e32 v74, 0, v74
	v_rcp_f32_e32 v75, v75
	ds_read_u16 v76, v106 offset:32
	s_waitcnt lgkmcnt(0)
	v_lshlrev_b32_e32 v76, 16, v76
	s_nop 1
	s_nop 1
	v_sqrt_f32_e32 v74, v74
	s_nop 0
	v_mul_f32_e32 v74, v75, v74
	v_mul_f32_e32 v74, v74, v76
	v_cvt_pk_bf16_f32 v74, v74, s0
	ds_write_b16 v123, v74 offset:38176
	v_add_f32_e32 v74, v164, v77
	v_mul_f32_e32 v74, 0xbfb8aa3b, v74
	v_exp_f32_e32 v74, v74
	s_nop 0
	v_add_f32_e32 v74, 1.0, v74
	s_nop 0
	v_rcp_f32_e32 v74, v74
	v_add_f32_e32 v75, v165, v177
	v_mul_f32_e32 v75, 0xbfb8aa3b, v75
	v_exp_f32_e32 v75, v75
	v_mul_f32_e32 v74, 0xc1000000, v74
	v_mul_f32_e32 v74, v166, v74
	v_mul_f32_e32 v74, 0x3fb8aa3b, v74
	v_add_f32_e32 v75, 1.0, v75
	v_exp_f32_e32 v74, v74
	v_mfma_f32_16x16x32_bf16 v[174:177], v[70:73], v[40:43], 0
	ds_write_b32 v120, v74 offset:33856
	v_fma_f32 v74, -v74, v74, 1.0
	v_max_f32_e32 v74, 0, v74
	v_rcp_f32_e32 v75, v75
	ds_read_u16 v76, v104 offset:32
	v_mfma_f32_16x16x32_bf16 v[174:177], v[66:69], v[56:59], v[174:177]
	s_waitcnt lgkmcnt(0)
	v_lshlrev_b32_e32 v76, 16, v76
	s_nop 1
	s_nop 1
	v_sqrt_f32_e32 v74, v74
	s_nop 0
	v_mul_f32_e32 v74, v75, v74
	v_mul_f32_e32 v74, v74, v76
	v_cvt_pk_bf16_f32 v74, v74, s0
	ds_write_b16 v124, v74 offset:38176
	v_mfma_f32_16x16x32_bf16 v[74:77], v[70:73], v[8:11], 0
	v_mfma_f32_16x16x32_bf16 v[74:77], v[66:69], v[24:27], v[74:77]
	s_nop 7
	v_add_f32_e32 v74, v167, v74
	v_mul_f32_e32 v74, 0xbfb8aa3b, v74
	v_exp_f32_e32 v74, v74
	s_nop 0
	v_add_f32_e32 v74, 1.0, v74
	s_nop 0
	v_rcp_f32_e32 v74, v74
	v_add_f32_e32 v105, v168, v174
	v_mul_f32_e32 v105, 0xbfb8aa3b, v105
	v_exp_f32_e32 v105, v105
	v_mul_f32_e32 v74, 0xc1000000, v74
	v_mul_f32_e32 v74, v169, v74
	v_mul_f32_e32 v74, 0x3fb8aa3b, v74
	v_add_f32_e32 v105, 1.0, v105
	v_exp_f32_e32 v74, v74
	ds_write_b32 v114, v74 offset:33920
	v_fma_f32 v74, -v74, v74, 1.0
	v_max_f32_e32 v74, 0, v74
	v_rcp_f32_e32 v105, v105
	ds_read_u16 v107, v110 offset:64
	s_waitcnt lgkmcnt(0)
	v_lshlrev_b32_e32 v107, 16, v107
	s_nop 1
	s_nop 1
	v_sqrt_f32_e32 v74, v74
	s_nop 0
	v_mul_f32_e32 v74, v105, v74
	v_mul_f32_e32 v74, v74, v107
	v_cvt_pk_bf16_f32 v74, v74, s0
	ds_write_b16 v121, v74 offset:38208
	v_add_f32_e32 v74, v167, v75
	v_mul_f32_e32 v74, 0xbfb8aa3b, v74
	v_exp_f32_e32 v74, v74
	s_nop 0
	v_add_f32_e32 v74, 1.0, v74
	s_nop 0
	v_rcp_f32_e32 v74, v74
	v_add_f32_e32 v75, v168, v175
	v_mul_f32_e32 v75, 0xbfb8aa3b, v75
	v_exp_f32_e32 v75, v75
	v_mul_f32_e32 v74, 0xc1000000, v74
	v_mul_f32_e32 v74, v169, v74
	v_mul_f32_e32 v74, 0x3fb8aa3b, v74
	v_add_f32_e32 v75, 1.0, v75
	v_exp_f32_e32 v74, v74
	ds_write_b32 v116, v74 offset:33920
	v_fma_f32 v74, -v74, v74, 1.0
	v_max_f32_e32 v74, 0, v74
	v_rcp_f32_e32 v75, v75
	ds_read_u16 v105, v108 offset:64
	s_waitcnt lgkmcnt(0)
	v_lshlrev_b32_e32 v105, 16, v105
	s_nop 1
	s_nop 1
	v_sqrt_f32_e32 v74, v74
	s_nop 0
	v_mul_f32_e32 v74, v75, v74
	v_mul_f32_e32 v74, v74, v105
	v_cvt_pk_bf16_f32 v74, v74, s0
	ds_write_b16 v122, v74 offset:38208
	v_add_f32_e32 v74, v167, v76
	v_mul_f32_e32 v74, 0xbfb8aa3b, v74
	v_exp_f32_e32 v74, v74
	s_nop 0
	v_add_f32_e32 v74, 1.0, v74
	s_nop 0
	v_rcp_f32_e32 v74, v74
	v_add_f32_e32 v75, v168, v176
	v_mul_f32_e32 v75, 0xbfb8aa3b, v75
	v_exp_f32_e32 v75, v75
	v_mul_f32_e32 v74, 0xc1000000, v74
	v_mul_f32_e32 v74, v169, v74
	v_mul_f32_e32 v74, 0x3fb8aa3b, v74
	v_add_f32_e32 v75, 1.0, v75
	v_exp_f32_e32 v74, v74
	ds_write_b32 v118, v74 offset:33920
	v_fma_f32 v74, -v74, v74, 1.0
	v_max_f32_e32 v74, 0, v74
	v_rcp_f32_e32 v75, v75
	ds_read_u16 v76, v106 offset:64
	s_waitcnt lgkmcnt(0)
	v_lshlrev_b32_e32 v76, 16, v76
	s_nop 1
	s_nop 1
	v_sqrt_f32_e32 v74, v74
	s_nop 0
	v_mul_f32_e32 v74, v75, v74
	v_mul_f32_e32 v74, v74, v76
	v_cvt_pk_bf16_f32 v74, v74, s0
	ds_write_b16 v123, v74 offset:38208
	v_add_f32_e32 v74, v167, v77
	v_mul_f32_e32 v74, 0xbfb8aa3b, v74
	v_exp_f32_e32 v74, v74
	s_nop 0
	v_add_f32_e32 v74, 1.0, v74
	s_nop 0
	v_rcp_f32_e32 v74, v74
	v_add_f32_e32 v75, v168, v177
	v_mul_f32_e32 v75, 0xbfb8aa3b, v75
	v_exp_f32_e32 v75, v75
	v_mul_f32_e32 v74, 0xc1000000, v74
	v_mul_f32_e32 v74, v169, v74
	v_mul_f32_e32 v74, 0x3fb8aa3b, v74
	v_add_f32_e32 v75, 1.0, v75
	v_exp_f32_e32 v74, v74
	ds_write_b32 v120, v74 offset:33920
	v_fma_f32 v74, -v74, v74, 1.0
	v_max_f32_e32 v74, 0, v74
	v_rcp_f32_e32 v75, v75
	ds_read_u16 v76, v104 offset:64
	s_waitcnt lgkmcnt(0)
	v_lshlrev_b32_e32 v76, 16, v76
	s_nop 1
	s_nop 1
	v_sqrt_f32_e32 v74, v74
	s_nop 0
	v_mul_f32_e32 v74, v75, v74
	v_mul_f32_e32 v74, v74, v76
	v_cvt_pk_bf16_f32 v74, v74, s0
	ds_write_b16 v124, v74 offset:38208
	v_mfma_f32_16x16x32_bf16 v[74:77], v[70:73], v[12:15], 0
	v_mfma_f32_16x16x32_bf16 v[74:77], v[66:69], v[28:31], v[74:77]
	v_mfma_f32_16x16x32_bf16 v[70:73], v[70:73], v[44:47], 0
	v_mfma_f32_16x16x32_bf16 v[66:69], v[66:69], v[60:63], v[70:73]
	s_waitcnt vmcnt(2)
	s_nop 5
	v_add_f32_e32 v70, v170, v74
	v_mul_f32_e32 v70, 0xbfb8aa3b, v70
	v_exp_f32_e32 v70, v70
	s_waitcnt vmcnt(1)
; __device__ __forceinline__ bf16_t f2bf(float f) { return (bf16_t)(cvt_pk_bf16(f, 0.f) & 0xffffu); }
; __device__ __forceinline__ float bf2f(bf16_t b) { return __uint_as_float(((unsigned)b) << 16); }
; __device__ __forceinline__ float sigmoidf_(float x) { return 1.0f / (1.0f + __expf(-x)); }
; __device__ __forceinline__ void wave_lds_fence() { asm volatile("s_waitcnt lgkmcnt(0)" ::: "memory"); __builtin_amdgcn_wave_barrier(); }
; template <bool FINAL>
; __device__ __forceinline__ void lru_item(const Ctx& C, int l, int item) {
;     ...
;             for (int dt = 0; dt < 4; ++dt) {
;                 f32x4 Da = {0.f, 0.f, 0.f, 0.f}, Dx = {0.f, 0.f, 0.f, 0.f};
;                 Da = __builtin_amdgcn_mfma_f32_16x16x32_bf16(xa0, Bw[0][dt][0], Da, 0, 0, 0); Da = __builtin_amdgcn_mfma_f32_16x16x32_bf16(xa1, Bw[0][dt][1], Da, 0, 0, 0);
;                 Dx = __builtin_amdgcn_mfma_f32_16x16x32_bf16(xa0, Bw[1][dt][0], Dx, 0, 0, 0); Dx = __builtin_amdgcn_mfma_f32_16x16x32_bf16(xa1, Bw[1][dt][1], Dx, 0, 0, 0);
; #pragma unroll
;                 for (int r = 0; r < 4; ++r) { const int tloc = 4 * quad + r, d = 16 * dt + fr;
;                     const float rg = sigmoidf_(Da[r] + bav[dt]), ig = sigmoidf_(Dx[r] + bxv[dt]), la = -8.0f * rg * spv[dt], a = __expf(la);
;                     const float x = bf2f(xc[(16 * tt + tloc) * XCP + n * 64 + d]);
;                     Al[tloc * 68 + d] = a; Ul[tloc * 68 + d] = f2bf(sqrtf(fmaxf(1.0f - a * a, 0.f)) * ig * x); }
;             }
;             wave_lds_fence();
; #pragma unroll
;             for (int j = 0; j < 16; ++j) { const int tloc = z ? 15 - j : j;
;                 const float a = Al[tloc * 68 + lane], u = bf2f(Ul[tloc * 68 + lane]);
;                 h = fmaf(a, h, u); Ap *= a;
;                 if (FINAL) Hz[(16 * tt + tloc) * 256 + n * 64 + lane] = f2bf(h); }
;             wave_lds_fence();
	v_add_f32_e32 v66, v171, v66
	v_mul_f32_e32 v66, 0xbfb8aa3b, v66
	v_exp_f32_e32 v66, v66
	v_add_f32_e32 v70, 1.0, v70
	v_add_f32_e32 v66, 1.0, v66
	v_add_f32_e32 v67, v171, v67
	v_mul_f32_e32 v67, 0xbfb8aa3b, v67
	v_rcp_f32_e32 v70, v70
	s_nop 0
	v_mul_f32_e32 v70, 0xc1000000, v70
	v_mul_f32_e32 v70, v172, v70
	v_mul_f32_e32 v70, 0x3fb8aa3b, v70
	v_exp_f32_e32 v70, v70
	ds_write_b32 v114, v70 offset:33984
	v_fma_f32 v70, -v70, v70, 1.0
	v_max_f32_e32 v70, 0, v70
	v_rcp_f32_e32 v66, v66
	ds_read_u16 v71, v110 offset:96
	v_exp_f32_e32 v67, v67
	s_waitcnt lgkmcnt(0)
	v_lshlrev_b32_e32 v71, 16, v71
	v_add_f32_e32 v67, 1.0, v67
	s_nop 0
	s_nop 1
	v_sqrt_f32_e32 v70, v70
	s_nop 0
	v_mul_f32_e32 v66, v66, v70
	v_mul_f32_e32 v66, v66, v71
	v_cvt_pk_bf16_f32 v66, v66, s0
	ds_write_b16 v121, v66 offset:38240
	v_add_f32_e32 v66, v170, v75
	v_mul_f32_e32 v66, 0xbfb8aa3b, v66
	v_exp_f32_e32 v66, v66
	s_nop 0
	v_add_f32_e32 v66, 1.0, v66
	s_nop 0
	v_rcp_f32_e32 v66, v66
	s_nop 0
	v_mul_f32_e32 v66, 0xc1000000, v66
	v_mul_f32_e32 v66, v172, v66
	v_mul_f32_e32 v66, 0x3fb8aa3b, v66
	v_exp_f32_e32 v66, v66
	ds_write_b32 v116, v66 offset:33984
	v_fma_f32 v66, -v66, v66, 1.0
	v_max_f32_e32 v66, 0, v66
	v_rcp_f32_e32 v67, v67
	ds_read_u16 v70, v108 offset:96
	s_waitcnt lgkmcnt(0)
	v_lshlrev_b32_e32 v70, 16, v70
	s_nop 1
	s_nop 1
	v_sqrt_f32_e32 v66, v66
	s_nop 0
	v_mul_f32_e32 v66, v67, v66
	v_mul_f32_e32 v66, v66, v70
	v_cvt_pk_bf16_f32 v66, v66, s0
	ds_write_b16 v122, v66 offset:38240
	v_add_f32_e32 v66, v170, v76
	v_mul_f32_e32 v66, 0xbfb8aa3b, v66
	v_exp_f32_e32 v66, v66
	s_nop 0
	v_add_f32_e32 v66, 1.0, v66
	s_nop 0
	v_rcp_f32_e32 v66, v66
	v_add_f32_e32 v67, v171, v68
	v_mul_f32_e32 v67, 0xbfb8aa3b, v67
	v_exp_f32_e32 v67, v67
	v_mul_f32_e32 v66, 0xc1000000, v66
	v_mul_f32_e32 v66, v172, v66
	v_mul_f32_e32 v66, 0x3fb8aa3b, v66
	v_add_f32_e32 v67, 1.0, v67
	v_exp_f32_e32 v66, v66
	ds_write_b32 v118, v66 offset:33984
	v_fma_f32 v66, -v66, v66, 1.0
	v_max_f32_e32 v66, 0, v66
	v_rcp_f32_e32 v67, v67
	ds_read_u16 v68, v106 offset:96
	s_waitcnt lgkmcnt(0)
	v_lshlrev_b32_e32 v68, 16, v68
	s_nop 1
	s_nop 1
	v_sqrt_f32_e32 v66, v66
	s_nop 0
	v_mul_f32_e32 v66, v67, v66
	v_mul_f32_e32 v66, v66, v68
	v_cvt_pk_bf16_f32 v66, v66, s0
	ds_write_b16 v123, v66 offset:38240
	v_add_f32_e32 v66, v170, v77
	v_mul_f32_e32 v66, 0xbfb8aa3b, v66
	v_exp_f32_e32 v66, v66
	s_nop 0
	v_add_f32_e32 v66, 1.0, v66
	s_nop 0
	v_rcp_f32_e32 v66, v66
	v_add_f32_e32 v67, v171, v69
	v_mul_f32_e32 v67, 0xbfb8aa3b, v67
	v_exp_f32_e32 v67, v67
	v_mul_f32_e32 v66, 0xc1000000, v66
	v_mul_f32_e32 v66, v172, v66
	v_mul_f32_e32 v66, 0x3fb8aa3b, v66
	v_add_f32_e32 v67, 1.0, v67
	v_exp_f32_e32 v66, v66
	ds_write_b32 v120, v66 offset:33984
	v_fma_f32 v66, -v66, v66, 1.0
	v_max_f32_e32 v66, 0, v66
	v_rcp_f32_e32 v67, v67
	ds_read_u16 v68, v104 offset:96
	s_waitcnt lgkmcnt(0)
	v_lshlrev_b32_e32 v68, 16, v68
	s_nop 1
	s_nop 1
	v_sqrt_f32_e32 v66, v66
	s_nop 0
	v_mul_f32_e32 v66, v67, v66
	v_mul_f32_e32 v66, v66, v68
	v_cvt_pk_bf16_f32 v66, v66, s0
	ds_write_b16 v124, v66 offset:38240
	s_waitcnt lgkmcnt(0)
	ds_read_b32 v178, v113 offset:33792
	ds_read_u16 v199, v125 offset:38144
	ds_read_b32 v179, v126 offset:33792
	ds_read_u16 v200, v147 offset:38144
	ds_read_b32 v180, v127 offset:33792
	ds_read_u16 v201, v148 offset:38144
	ds_read_b32 v181, v128 offset:33792
	ds_read_u16 v202, v149 offset:38144
	ds_read_b32 v183, v129 offset:33792
	ds_read_u16 v203, v150 offset:38144
	ds_read_b32 v188, v130 offset:33792
	ds_read_u16 v204, v151 offset:38144
	ds_read_b32 v189, v131 offset:33792
	ds_read_u16 v205, v152 offset:38144
	ds_read_b32 v190, v132 offset:33792
	ds_read_u16 v206, v153 offset:38144
	ds_read_b32 v191, v133 offset:33792
	ds_read_u16 v207, v154 offset:38144
	ds_read_b32 v192, v134 offset:33792
	ds_read_u16 v208, v155 offset:38144
	ds_read_b32 v193, v135 offset:33792
	ds_read_u16 v209, v156 offset:38144
	ds_read_b32 v194, v136 offset:33792
	ds_read_u16 v210, v157 offset:38144
	ds_read_b32 v195, v137 offset:33792
	ds_read_u16 v211, v158 offset:38144
	ds_read_b32 v196, v138 offset:33792
	ds_read_u16 v212, v159 offset:38144
	ds_read_b32 v197, v139 offset:33792
	ds_read_u16 v213, v160 offset:38144
	ds_read_b32 v198, v140 offset:33792
	ds_read_u16 v214, v161 offset:38144
	s_waitcnt lgkmcnt(15)
; __device__ __forceinline__ bf16_t f2bf(float f) { return (bf16_t)(cvt_pk_bf16(f, 0.f) & 0xffffu); }
; __device__ __forceinline__ float bf2f(bf16_t b) { return __uint_as_float(((unsigned)b) << 16); }
; __device__ __forceinline__ void wave_lds_fence() { asm volatile("s_waitcnt lgkmcnt(0)" ::: "memory"); __builtin_amdgcn_wave_barrier(); }
; template <bool FINAL>
; __device__ __forceinline__ void lru_item(const Ctx& C, int l, int item) {
;     ...
; #pragma unroll
;             for (int j = 0; j < 16; ++j) { const int tloc = z ? 15 - j : j;
;                 const float a = Al[tloc * 68 + lane], u = bf2f(Ul[tloc * 68 + lane]);
;                 h = fmaf(a, h, u); Ap *= a;
;                 if (FINAL) Hz[(16 * tt + tloc) * 256 + n * 64 + lane] = f2bf(h); }
;             wave_lds_fence();
	v_lshlrev_b32_e32 v66, 16, v199
	s_waitcnt vmcnt(0)
	v_fmac_f32_e32 v66, v178, v173
	v_cvt_pk_bf16_f32 v67, v66, s0
	s_or_b32 s0, s52, s13
	v_lshl_add_u32 v68, s0, 9, v141
	ds_write_b16 v68, v67
	s_waitcnt lgkmcnt(15)
	v_lshlrev_b32_e32 v67, 16, v200
	v_fmac_f32_e32 v67, v179, v66
	v_cvt_pk_bf16_f32 v66, v67, s0
	s_or_b32 s0, s52, s14
	v_lshl_add_u32 v68, s0, 9, v141
	ds_write_b16 v68, v66
	s_waitcnt lgkmcnt(15)
	v_lshlrev_b32_e32 v68, 16, v201
	v_fmac_f32_e32 v68, v180, v67
	v_cvt_pk_bf16_f32 v66, v68, s0
	s_or_b32 s0, s52, s15
	v_lshl_add_u32 v67, s0, 9, v141
	ds_write_b16 v67, v66
	s_waitcnt lgkmcnt(15)
	v_lshlrev_b32_e32 v67, 16, v202
	v_fmac_f32_e32 v67, v181, v68
	v_cvt_pk_bf16_f32 v66, v67, s0
	s_or_b32 s0, s52, s16
	v_lshl_add_u32 v68, s0, 9, v141
	ds_write_b16 v68, v66
	s_waitcnt lgkmcnt(15)
	v_lshlrev_b32_e32 v68, 16, v203
	v_fmac_f32_e32 v68, v183, v67
	v_cvt_pk_bf16_f32 v66, v68, s0
	s_or_b32 s0, s52, s17
	v_lshl_add_u32 v67, s0, 9, v141
	ds_write_b16 v67, v66
	s_waitcnt lgkmcnt(15)
	v_lshlrev_b32_e32 v67, 16, v204
	v_fmac_f32_e32 v67, v188, v68
	v_cvt_pk_bf16_f32 v66, v67, s0
	s_or_b32 s0, s52, s18
	v_lshl_add_u32 v68, s0, 9, v141
	ds_write_b16 v68, v66
	s_waitcnt lgkmcnt(15)
	v_lshlrev_b32_e32 v68, 16, v205
	v_fmac_f32_e32 v68, v189, v67
	v_cvt_pk_bf16_f32 v66, v68, s0
	s_or_b32 s0, s52, s19
	v_lshl_add_u32 v67, s0, 9, v141
	ds_write_b16 v67, v66
	s_waitcnt lgkmcnt(15)
	v_lshlrev_b32_e32 v67, 16, v206
	v_fmac_f32_e32 v67, v190, v68
	v_cvt_pk_bf16_f32 v66, v67, s0
	s_or_b32 s0, s52, s20
	v_lshl_add_u32 v68, s0, 9, v141
	ds_write_b16 v68, v66
	s_waitcnt lgkmcnt(15)
	v_lshlrev_b32_e32 v68, 16, v207
	v_fmac_f32_e32 v68, v191, v67
	v_cvt_pk_bf16_f32 v66, v68, s0
	s_or_b32 s0, s52, s21
	v_lshl_add_u32 v67, s0, 9, v141
	ds_write_b16 v67, v66
	s_waitcnt lgkmcnt(15)
	v_lshlrev_b32_e32 v67, 16, v208
	v_fmac_f32_e32 v67, v192, v68
	v_cvt_pk_bf16_f32 v66, v67, s0
	s_or_b32 s0, s52, s36
	v_lshl_add_u32 v68, s0, 9, v141
	ds_write_b16 v68, v66
	s_waitcnt lgkmcnt(15)
	v_lshlrev_b32_e32 v68, 16, v209
	v_fmac_f32_e32 v68, v193, v67
	v_cvt_pk_bf16_f32 v66, v68, s0
	s_or_b32 s0, s52, s38
	v_lshl_add_u32 v67, s0, 9, v141
	ds_write_b16 v67, v66
	s_waitcnt lgkmcnt(15)
	v_lshlrev_b32_e32 v67, 16, v210
	v_fmac_f32_e32 v67, v194, v68
	v_cvt_pk_bf16_f32 v66, v67, s0
	s_or_b32 s0, s52, s39
	v_lshl_add_u32 v68, s0, 9, v141
	ds_write_b16 v68, v66
	s_waitcnt lgkmcnt(15)
	v_lshlrev_b32_e32 v68, 16, v211
	v_fmac_f32_e32 v68, v195, v67
	v_cvt_pk_bf16_f32 v66, v68, s0
	s_or_b32 s0, s52, s42
	v_lshl_add_u32 v67, s0, 9, v141
	ds_write_b16 v67, v66
	s_waitcnt lgkmcnt(15)
	v_lshlrev_b32_e32 v67, 16, v212
	v_fmac_f32_e32 v67, v196, v68
	v_cvt_pk_bf16_f32 v66, v67, s0
	s_or_b32 s0, s52, s43
	v_lshl_add_u32 v68, s0, 9, v141
	ds_write_b16 v68, v66
	s_waitcnt lgkmcnt(15)
	v_lshlrev_b32_e32 v66, 16, v213
	v_fmac_f32_e32 v66, v197, v67
	v_cvt_pk_bf16_f32 v67, v66, s0
	s_or_b32 s0, s52, s44
	v_lshl_add_u32 v68, s0, 9, v141
	ds_write_b16 v68, v67
	s_waitcnt lgkmcnt(15)
	v_lshlrev_b32_e32 v173, 16, v214
	v_fmac_f32_e32 v173, v198, v66
	v_cvt_pk_bf16_f32 v66, v173, s0
	s_or_b32 s0, s52, s45
	v_lshl_add_u32 v67, s0, 9, v141
	ds_write_b16 v67, v66
	s_waitcnt lgkmcnt(0)
	s_cmp_eq_u32 s9, 4
	s_cbranch_scc0 .LBB0_681
	s_add_i32 s0, s8, s49
	s_ashr_i32 s1, s0, 31
	v_mov_b32_e32 v4, v99
	s_lshl_b64 s[8:9], s[0:1], 10
	s_lshl_b64 s[0:1], s[0:1], 9
	s_waitcnt lgkmcnt(0)
	s_barrier
	v_lshl_add_u64 v[0:1], v[100:101], 0, s[8:9]
	v_ashrrev_i32_e32 v5, 31, v4
	v_lshl_add_u64 v[2:3], v[102:103], 0, s[0:1]
	v_lshl_add_u32 v8, v4, 1, v143
	v_lshlrev_b64 v[4:5], 1, v[4:5]
	s_mov_b32 s0, 0
